# same tail split; W2D conversion split 25% in the P5 tail / 75% in the P9 tail
# baseline (speedup 1.0000x reference)
.Ld1b_268:
	s_cmpk_gt_i32 s61, 0xc5f
	s_cbranch_scc1 .Ld1b_end
	s_cmpk_lt_i32 s61, 0x840
	s_cbranch_scc1 .Ld1b_267
	s_cmpk_gt_i32 s61, 0xaff
	s_mov_b64 s[0:1], -1
	s_cbranch_scc0 .Ld1b_314
	s_lshl_b32 s0, s21, 2
	s_and_b32 s10, s0, 0xf80
	s_cmpk_gt_u32 s61, 0x107f
	s_mov_b64 s[0:1], -1
	s_cbranch_scc0 .Ld1b_309
	s_cmpk_gt_u32 s61, 0x167f
	s_cbranch_scc0 .Ld1b_280
	s_cmpk_gt_u32 s61, 0x187f
	s_cbranch_scc0 .Ld1b_275
	s_lshr_b32 s8, s21, 5
	s_lshr_b32 s4, s20, 7
	s_lshl_b64 s[0:1], s[4:5], 20
	s_and_b32 s4, s8, 15
	s_lshl_b32 s4, s4, 7
	s_or_b32 s0, s0, s4
	s_and_b32 s4, s23, 0x1c0
	v_or_b32_e32 v2, s4, v58
	v_lshl_or_b32 v42, v2, 11, s0
	v_mov_b32_e32 v43, s1
	v_or_b32_e32 v2, s4, v59
	v_lshl_add_u64 v[28:29], v[12:13], 0, v[42:43]
	v_lshl_or_b32 v42, v2, 11, s0
	v_or_b32_e32 v2, s4, v60
	v_lshl_add_u64 v[30:31], v[12:13], 0, v[42:43]
	v_lshl_or_b32 v42, v2, 11, s0
	v_or_b32_e32 v2, s4, v61
	v_lshl_add_u64 v[32:33], v[12:13], 0, v[42:43]
	v_lshl_or_b32 v42, v2, 11, s0
	v_or_b32_e32 v2, s4, v62
	v_lshl_add_u64 v[34:35], v[12:13], 0, v[42:43]
	v_lshl_or_b32 v42, v2, 11, s0
	v_or_b32_e32 v2, s4, v63
	v_lshl_add_u64 v[36:37], v[12:13], 0, v[42:43]
	v_lshl_or_b32 v42, v2, 11, s0
	v_or_b32_e32 v2, s4, v64
	v_lshl_add_u64 v[38:39], v[12:13], 0, v[42:43]
	v_lshl_or_b32 v42, v2, 11, s0
	v_or_b32_e32 v2, s4, v1
	v_lshl_add_u64 v[40:41], v[12:13], 0, v[42:43]
	v_lshl_or_b32 v42, v2, 11, s0
	v_lshl_add_u64 v[42:43], v[12:13], 0, v[42:43]
	s_mov_b64 s[0:1], 0
	v_mov_b32_e32 v2, v57

.Ld1c_268:
	s_cmpk_gt_i32 s61, 0xc5f
	s_mov_b64 s[0:1], -1
	s_cbranch_scc0 .Ld1c_267
	s_lshl_b32 s0, s21, 2
	s_and_b32 s10, s0, 0xf80
	s_cmpk_gt_u32 s61, 0x107f
	s_mov_b64 s[0:1], -1
	s_cbranch_scc0 .Ld1c_309
	s_branch .Ld1c_end
	s_cmpk_gt_u32 s61, 0x167f
	s_cbranch_scc0 .Ld1c_280
	s_cmpk_gt_u32 s61, 0x187f
	s_cbranch_scc0 .Ld1c_275
	s_lshr_b32 s8, s21, 5
	s_lshr_b32 s4, s20, 7
	s_lshl_b64 s[0:1], s[4:5], 20
	s_and_b32 s4, s8, 15
	s_lshl_b32 s4, s4, 7
	s_or_b32 s0, s0, s4
	s_and_b32 s4, s23, 0x1c0
	v_or_b32_e32 v2, s4, v58
	v_lshl_or_b32 v42, v2, 11, s0
	v_mov_b32_e32 v43, s1
	v_or_b32_e32 v2, s4, v59
	v_lshl_add_u64 v[28:29], v[12:13], 0, v[42:43]
	v_lshl_or_b32 v42, v2, 11, s0
	v_or_b32_e32 v2, s4, v60
	v_lshl_add_u64 v[30:31], v[12:13], 0, v[42:43]
	v_lshl_or_b32 v42, v2, 11, s0
	v_or_b32_e32 v2, s4, v61
	v_lshl_add_u64 v[32:33], v[12:13], 0, v[42:43]
	v_lshl_or_b32 v42, v2, 11, s0
	v_or_b32_e32 v2, s4, v62
	v_lshl_add_u64 v[34:35], v[12:13], 0, v[42:43]
	v_lshl_or_b32 v42, v2, 11, s0
	v_or_b32_e32 v2, s4, v63
	v_lshl_add_u64 v[36:37], v[12:13], 0, v[42:43]
	v_lshl_or_b32 v42, v2, 11, s0
	v_or_b32_e32 v2, s4, v64
	v_lshl_add_u64 v[38:39], v[12:13], 0, v[42:43]
	v_lshl_or_b32 v42, v2, 11, s0
	v_or_b32_e32 v2, s4, v1
	v_lshl_add_u64 v[40:41], v[12:13], 0, v[42:43]
	v_lshl_or_b32 v42, v2, 11, s0
	v_lshl_add_u64 v[42:43], v[12:13], 0, v[42:43]
	s_mov_b64 s[0:1], 0
	v_mov_b32_e32 v2, v57
